# v37 plus: norm phase (runtime-nsplit copy), sample-row workgroups touch the row's X, split-K slices and shift/scale vectors ahead of the table-build loads
# baseline (speedup 1.0000x reference)
; #define LAS __attribute__((address_space(3)))
; #define INP(i) ((const float*)(const GASP float*)kargs()[(i)])
; __device__ __forceinline__ void phase_norm(const Frame& F, int l, int which, int nsplit) {
;     ...
;     const float* nw = INP(I_NW) + (size_t)(l * 3 + which) * D; const float* mbase = MOD + (size_t)l * NMODW + (size_t)(3 * which) * D;
;     LAS float* T = (LAS float*)F.lds;
;     const bool fast = (F.NGW == 2048); h16x8 pre[2][4];
;     if (fast) {
; #pragma unroll
;         for (int q = 0; q < 2; ++q) { const h16x8* xp = (const h16x8*)(X + (size_t)(F.gw + 2048 * q) * D) + F.lane;
; #pragma unroll
;             for (int jx = 0; jx < 4; ++jx) pre[q][jx] = xp[64 * jx]; } }
;     { f32x4 tw, tsh[4], tsc[4]; const int c4 = F.tid * 4;
;       tw = *(const f32x4*)(nw + c4);
; #pragma unroll
;       for (int bb = 0; bb < 4; ++bb) { tsh[bb] = *(const f32x4*)(mbase + (size_t)bb * MODLD + c4); tsc[bb] = *(const f32x4*)(mbase + (size_t)bb * MODLD + D + c4); }
; #pragma unroll
;       for (int bb = 0; bb < 4; ++bb) { *(LAS f32x4*)(T + (bb * 2) * 2048 + c4) = tw * (tsc[bb] + 1.0f); *(LAS f32x4*)(T + (bb * 2 + 1) * 2048 + c4) = tsh[bb]; } }
;     for (int sr = F.vcu; sr < TS; sr += F.G) { float rs; const f32x4 v = sample_row_coop(F, X, PART, sr, nsplit, (LAS float*)(F.lds + 65536), rs);
;         const int c = F.wave * 256 + F.lane * 4; const float* mp = mbase + (size_t)(4 + sr) * MODLD; const f32x4 w = *(const f32x4*)(nw + c), sh = *(const f32x4*)(mp + c), sc = *(const f32x4*)(mp + D + c);
.LBB0_2205:
	v_readlane_b32 s14, v246, 30
	v_readlane_b32 s15, v246, 31
	s_and_b64 s[14:15], s[14:15], exec
	v_readlane_b32 s11, v247, 53
	s_cselect_b32 s6, 0, 2
	s_add_u32 s26, s54, 0x44e00000
	s_mul_i32 s11, s11, 3
	s_addc_u32 s27, s55, 0
	s_add_i32 s11, s6, s11
	s_lshl_b32 s11, s11, 13
	s_waitcnt lgkmcnt(0)
	s_add_u32 s14, s40, s11
	s_addc_u32 s15, s41, 0
	v_readlane_b32 s11, v247, 59
	s_add_u32 s11, s22, s11
	s_addc_u32 s12, s23, 0
	s_mulk_i32 s6, 0x6000
	s_add_u32 s6, s11, s6
	s_addc_u32 s11, s12, 0
	s_add_u32 s56, s6, 0x3c400000
	v_readlane_b32 s6, v248, 4
	s_addc_u32 s57, s11, 0
	s_cmpk_gt_i32 s50, 0x7f
	v_lshl_add_u32 v28, v64, 2, s6
	v_ashrrev_i32_e32 v29, 31, v28
	v_lshlrev_b64 v[4:5], 2, v[28:29]
	v_lshl_add_u64 v[102:103], s[56:57], 0, v[4:5]
	v_add_co_u32_e32 v8, vcc, s89, v102
	s_mov_b32 s6, 0x4a000
	s_nop 0
	v_addc_co_u32_e32 v9, vcc, 0, v103, vcc
	v_add_co_u32_e32 v12, vcc, s21, v102
	v_lshl_add_u64 v[30:31], s[14:15], 0, v[4:5]
	s_nop 0
	v_addc_co_u32_e32 v13, vcc, 0, v103, vcc
	v_add_co_u32_e32 v16, vcc, s6, v102
	s_mov_b32 s6, 0x90000
	s_nop 0
	v_addc_co_u32_e32 v17, vcc, 0, v103, vcc
	v_add_co_u32_e32 v20, vcc, s6, v102
	s_mov_b32 s6, 0x92000
	s_nop 0
	v_addc_co_u32_e32 v21, vcc, 0, v103, vcc
	s_cbranch_scc1 .Lnorm_touchA_skip
	v_mov_b32_e32 v250, s50
	v_mov_b32_e32 v251, 0
	v_add_u32_e32 v250, 0x2000, v250
	v_lshlrev_b64 v[250:251], 12, v[250:251]
	v_lshl_add_u64 v[250:251], v[28:29], 1, v[250:251]
	v_lshl_add_u64 v[250:251], v[250:251], 0, s[44:45]
	global_load_dword v249, v[250:251], off
	v_mov_b32_e32 v250, s50
	v_mov_b32_e32 v251, 0
	v_lshlrev_b64 v[250:251], 13, v[250:251]
	v_lshl_add_u64 v[250:251], v[28:29], 2, v[250:251]
	v_lshl_add_u64 v[250:251], v[250:251], 0, s[42:43]
	s_mov_b64 s[98:99], 0x6e767000
	v_lshl_add_u64 v[250:251], v[250:251], 0, s[98:99]
	s_mov_b64 s[98:99], 0x100000
	global_load_dword v249, v[250:251], off
	v_lshl_add_u64 v[250:251], v[250:251], 0, s[98:99]
	global_load_dword v249, v[250:251], off
	v_lshl_add_u64 v[250:251], v[250:251], 0, s[98:99]
	global_load_dword v249, v[250:251], off
	v_lshl_add_u64 v[250:251], v[250:251], 0, s[98:99]
	global_load_dword v249, v[250:251], off
	v_lshl_add_u64 v[250:251], v[250:251], 0, s[98:99]
	global_load_dword v249, v[250:251], off
	v_lshl_add_u64 v[250:251], v[250:251], 0, s[98:99]
	global_load_dword v249, v[250:251], off
	v_lshl_add_u64 v[250:251], v[250:251], 0, s[98:99]
	global_load_dword v249, v[250:251], off
	v_mov_b32_e32 v250, s50
	v_add_u32_e32 v250, 4, v250
	v_mul_u32_u24_e32 v250, 0x48000, v250
	v_mov_b32_e32 v251, 0
	v_lshl_add_u64 v[250:251], v[250:251], 0, s[56:57]
	v_lshl_add_u64 v[250:251], v[28:29], 2, v[250:251]
	global_load_dword v249, v[250:251], off
	s_mov_b32 s98, s89
	s_mov_b32 s99, 0
	v_lshl_add_u64 v[250:251], v[250:251], 0, s[98:99]
	global_load_dword v249, v[250:251], off
.Lnorm_touchA_skip:
	global_load_dwordx4 v[8:11], v[8:9], off
	v_add_co_u32_e32 v24, vcc, s6, v102
	global_load_dwordx4 v[0:3], v[30:31], off
	s_nop 0
	v_addc_co_u32_e32 v25, vcc, 0, v103, vcc
	s_mov_b32 s6, 0xd8000
	global_load_dwordx4 v[16:19], v[16:17], off
	v_add_co_u32_e32 v98, vcc, s6, v102
	global_load_dwordx4 v[4:7], v[102:103], off
	s_nop 0
	v_addc_co_u32_e32 v99, vcc, 0, v103, vcc
	s_mov_b32 s6, 0xda000
	global_load_dwordx4 v[24:27], v[24:25], off
	v_lshl_add_u32 v65, v28, 2, 0
	global_load_dwordx4 v[98:101], v[98:99], off
	v_add_co_u32_e32 v102, vcc, s6, v102
	global_load_dwordx4 v[12:15], v[12:13], off
	s_nop 0
	v_addc_co_u32_e32 v103, vcc, 0, v103, vcc
	global_load_dwordx4 v[102:105], v[102:103], off
	s_waitcnt vmcnt(7)
	v_pk_add_f32 v[10:11], v[10:11], 1.0 op_sel_hi:[1,0]
	global_load_dwordx4 v[20:23], v[20:21], off
	v_pk_add_f32 v[8:9], v[8:9], 1.0 op_sel_hi:[1,0]
	s_waitcnt vmcnt(7)
	v_pk_mul_f32 v[10:11], v[2:3], v[10:11]
	v_pk_mul_f32 v[8:9], v[0:1], v[8:9]
	ds_write_b128 v65, v[8:11]
	s_waitcnt vmcnt(5)
	ds_write_b128 v65, v[4:7] offset:8192
	v_pk_add_f32 v[4:5], v[18:19], 1.0 op_sel_hi:[1,0]
	v_pk_add_f32 v[8:9], v[16:17], 1.0 op_sel_hi:[1,0]
	v_pk_mul_f32 v[6:7], v[2:3], v[4:5]
	v_pk_mul_f32 v[4:5], v[0:1], v[8:9]
	ds_write_b128 v65, v[4:7] offset:16384
	s_waitcnt vmcnt(2)
	ds_write_b128 v65, v[12:15] offset:24576
	v_pk_add_f32 v[4:5], v[26:27], 1.0 op_sel_hi:[1,0]
	v_pk_add_f32 v[8:9], v[24:25], 1.0 op_sel_hi:[1,0]
	v_pk_mul_f32 v[6:7], v[2:3], v[4:5]
	v_pk_mul_f32 v[4:5], v[0:1], v[8:9]
	ds_write_b128 v65, v[4:7] offset:32768
	s_waitcnt vmcnt(0)
	ds_write_b128 v65, v[20:23] offset:40960
	v_pk_add_f32 v[4:5], v[104:105], 1.0 op_sel_hi:[1,0]
	v_pk_add_f32 v[6:7], v[102:103], 1.0 op_sel_hi:[1,0]
	v_pk_mul_f32 v[2:3], v[2:3], v[4:5]
	v_pk_mul_f32 v[0:1], v[0:1], v[6:7]
	ds_write_b128 v65, v[0:3] offset:49152
	ds_write_b128 v65, v[98:101] offset:57344
	s_cbranch_scc1 .LBB0_2222
	v_readlane_b32 s14, v246, 30
	v_readlane_b32 s15, v246, 31
	s_and_b64 s[14:15], s[14:15], exec
	v_readlane_b32 s6, v246, 24
	v_readlane_b32 s11, v246, 25
	s_cselect_b32 s6, s6, s11
	v_readlane_b32 s11, v247, 53
	v_readlane_b32 s12, v246, 32
	s_or_b32 s11, s12, s11
	s_cmp_lg_u32 s11, 0
	s_cselect_b64 s[58:59], -1, 0
	s_cmp_gt_u32 s6, 2
	s_cselect_b64 s[60:61], -1, 0
	s_cmp_gt_u32 s6, 3
	s_cselect_b64 s[62:63], -1, 0
	s_cmp_gt_u32 s6, 4
	s_cselect_b64 s[64:65], -1, 0
	s_cmp_gt_u32 s6, 5
	s_cselect_b64 s[66:67], -1, 0
	s_cmp_eq_u32 s6, 7
	s_cselect_b64 s[68:69], -1, 0
	s_ashr_i32 s51, s50, 31
	s_lshl_b64 s[14:15], s[50:51], 13
	s_add_u32 s14, s42, s14
	s_addc_u32 s15, s43, s15
	v_lshl_add_u64 v[0:1], v[28:29], 2, s[14:15]
	s_mov_b64 s[14:15], 0x6ed67000
	v_lshl_add_u64 v[98:99], v[0:1], 0, s[14:15]
	s_add_i32 s14, s50, 0x2000
	s_ashr_i32 s15, s14, 31
	s_ashr_i32 s49, s48, 31
	s_lshl_b64 s[14:15], s[14:15], 12
	v_cmp_eq_u32_e64 s[40:41], 0, v64
	s_lshl_b64 s[70:71], s[48:49], 13
	v_lshl_add_u64 v[100:101], v[28:29], 1, s[14:15]
	s_lshl_b64 s[72:73], s[48:49], 12
	s_mov_b32 s6, s50
	s_branch .LBB0_2208
